# NSA top-16: items with fewer than 17 visible blocks take every visible block directly (exact) and skip the threshold search
# speedup vs baseline: 1.0008x; 1.0008x over previous
.LBB0_244:
	v_mov_b32_e32 v0, v222
	s_waitcnt lgkmcnt(0)
	s_barrier
	s_nop 0
	v_lshlrev_b32_e32 v0, 2, v0
	v_xor_b32_e32 v0, 0x80, v0
	ds_bpermute_b32 v0, v0, v187
	s_waitcnt lgkmcnt(0)
	v_add_f32_e32 v0, v187, v0
	v_div_scale_f32 v66, s[0:1], v0, v0, 1.0
	v_rcp_f32_e32 v67, v66
	v_div_scale_f32 v68, vcc, 1.0, v0, 1.0
	v_fma_f32 v69, -v66, v67, 1.0
	v_fmac_f32_e32 v67, v69, v67
	v_mul_f32_e32 v69, v68, v67
	v_fma_f32 v70, -v66, v69, v68
	v_fmac_f32_e32 v69, v70, v67
	v_fma_f32 v66, -v66, v69, v68
	v_div_fmas_f32 v66, v66, v67, v69
	v_div_fixup_f32 v66, v66, v0, 1.0
	v_cmp_lt_f32_e32 vcc, 0, v0
	s_nop 1
	v_cndmask_b32_e32 v140, 0, v66, vcc
	v_mul_f32_e32 v0, v50, v140
	v_mul_f32_e32 v226, v51, v140
	v_mul_f32_e32 v227, v52, v140
	v_mov_b32_dpp v0, v0 row_ror:8 row_mask:0xf bank_mask:0xf
	v_mov_b32_dpp v226, v226 row_ror:8 row_mask:0xf bank_mask:0xf
	v_mov_b32_dpp v227, v227 row_ror:8 row_mask:0xf bank_mask:0xf
	v_fmac_f32_e32 v0, v50, v140
	v_fmac_f32_e32 v226, v51, v140
	v_fmac_f32_e32 v227, v52, v140
	v_mov_b32_e32 v50, v0
	v_mov_b32_e32 v51, v226
	v_mov_b32_e32 v52, v227
	v_permlane16_swap_b32_e32 v50, v0
	v_permlane16_swap_b32_e32 v51, v226
	v_permlane16_swap_b32_e32 v52, v227
	v_add_f32_e32 v0, v50, v0
	v_add_f32_e32 v226, v51, v226
	v_add_f32_e32 v227, v52, v227
	s_and_saveexec_b64 s[0:1], s[4:5]
	ds_write_b32 v177, v0 offset:36864
	ds_write_b32 v177, v226 offset:36868
	ds_write_b32 v177, v227 offset:36872
	s_or_b64 exec, exec, s[0:1]
	v_mul_f32_e32 v0, v53, v140
	v_mul_f32_e32 v226, v54, v140
	v_mul_f32_e32 v227, v55, v140
	v_mov_b32_dpp v0, v0 row_ror:8 row_mask:0xf bank_mask:0xf
	v_mov_b32_dpp v226, v226 row_ror:8 row_mask:0xf bank_mask:0xf
	v_mov_b32_dpp v227, v227 row_ror:8 row_mask:0xf bank_mask:0xf
	v_fmac_f32_e32 v0, v53, v140
	v_fmac_f32_e32 v226, v54, v140
	v_fmac_f32_e32 v227, v55, v140
	v_mov_b32_e32 v53, v0
	v_mov_b32_e32 v54, v226
	v_mov_b32_e32 v55, v227
	v_permlane16_swap_b32_e32 v53, v0
	v_permlane16_swap_b32_e32 v54, v226
	v_permlane16_swap_b32_e32 v55, v227
	v_add_f32_e32 v0, v53, v0
	v_add_f32_e32 v226, v54, v226
	v_add_f32_e32 v227, v55, v227
	s_and_saveexec_b64 s[0:1], s[4:5]
	ds_write_b32 v177, v0 offset:36876
	ds_write_b32 v177, v226 offset:36896
	ds_write_b32 v177, v227 offset:36900
	s_or_b64 exec, exec, s[0:1]
	v_mul_f32_e32 v0, v56, v140
	v_mul_f32_e32 v226, v57, v140
	v_mul_f32_e32 v227, v58, v140
	v_mov_b32_dpp v0, v0 row_ror:8 row_mask:0xf bank_mask:0xf
	v_mov_b32_dpp v226, v226 row_ror:8 row_mask:0xf bank_mask:0xf
	v_mov_b32_dpp v227, v227 row_ror:8 row_mask:0xf bank_mask:0xf
	v_fmac_f32_e32 v0, v56, v140
	v_fmac_f32_e32 v226, v57, v140
	v_fmac_f32_e32 v227, v58, v140
	v_mov_b32_e32 v56, v0
	v_mov_b32_e32 v57, v226
	v_mov_b32_e32 v58, v227
	v_permlane16_swap_b32_e32 v56, v0
	v_permlane16_swap_b32_e32 v57, v226
	v_permlane16_swap_b32_e32 v58, v227
	v_add_f32_e32 v0, v56, v0
	v_add_f32_e32 v226, v57, v226
	v_add_f32_e32 v227, v58, v227
	s_and_saveexec_b64 s[0:1], s[4:5]
	ds_write_b32 v177, v0 offset:36904
	ds_write_b32 v177, v226 offset:36908
	ds_write_b32 v177, v227 offset:36928
	s_or_b64 exec, exec, s[0:1]
	v_mul_f32_e32 v0, v59, v140
	v_mul_f32_e32 v226, v60, v140
	v_mul_f32_e32 v227, v61, v140
	v_mov_b32_dpp v0, v0 row_ror:8 row_mask:0xf bank_mask:0xf
	v_mov_b32_dpp v226, v226 row_ror:8 row_mask:0xf bank_mask:0xf
	v_mov_b32_dpp v227, v227 row_ror:8 row_mask:0xf bank_mask:0xf
	v_fmac_f32_e32 v0, v59, v140
	v_fmac_f32_e32 v226, v60, v140
	v_fmac_f32_e32 v227, v61, v140
	v_mov_b32_e32 v59, v0
	v_mov_b32_e32 v60, v226
	v_mov_b32_e32 v61, v227
	v_permlane16_swap_b32_e32 v59, v0
	v_permlane16_swap_b32_e32 v60, v226
	v_permlane16_swap_b32_e32 v61, v227
	v_add_f32_e32 v0, v59, v0
	v_add_f32_e32 v226, v60, v226
	v_add_f32_e32 v227, v61, v227
	s_and_saveexec_b64 s[0:1], s[4:5]
	ds_write_b32 v177, v0 offset:36932
	ds_write_b32 v177, v226 offset:36936
	ds_write_b32 v177, v227 offset:36940
	s_or_b64 exec, exec, s[0:1]
	v_mul_f32_e32 v0, v62, v140
	v_mul_f32_e32 v226, v63, v140
	v_mul_f32_e32 v227, v64, v140
	v_mov_b32_dpp v0, v0 row_ror:8 row_mask:0xf bank_mask:0xf
	v_mov_b32_dpp v226, v226 row_ror:8 row_mask:0xf bank_mask:0xf
	v_mov_b32_dpp v227, v227 row_ror:8 row_mask:0xf bank_mask:0xf
	v_fmac_f32_e32 v0, v62, v140
	v_fmac_f32_e32 v226, v63, v140
	v_fmac_f32_e32 v227, v64, v140
	v_mov_b32_e32 v62, v0
	v_mov_b32_e32 v63, v226
	v_mov_b32_e32 v64, v227
	v_permlane16_swap_b32_e32 v62, v0
	v_permlane16_swap_b32_e32 v63, v226
	v_permlane16_swap_b32_e32 v64, v227
	v_add_f32_e32 v0, v62, v0
	v_add_f32_e32 v226, v63, v226
	v_add_f32_e32 v227, v64, v227
	s_and_saveexec_b64 s[0:1], s[4:5]
	ds_write_b32 v177, v0 offset:36960
	ds_write_b32 v177, v226 offset:36964
	ds_write_b32 v177, v227 offset:36968
	s_or_b64 exec, exec, s[0:1]
	v_mul_f32_e32 v0, v65, v140
	v_mul_f32_e32 v226, v34, v140
	v_mul_f32_e32 v227, v35, v140
	v_mov_b32_dpp v0, v0 row_ror:8 row_mask:0xf bank_mask:0xf
	v_mov_b32_dpp v226, v226 row_ror:8 row_mask:0xf bank_mask:0xf
	v_mov_b32_dpp v227, v227 row_ror:8 row_mask:0xf bank_mask:0xf
	v_fmac_f32_e32 v0, v65, v140
	v_fmac_f32_e32 v226, v34, v140
	v_fmac_f32_e32 v227, v35, v140
	v_mov_b32_e32 v65, v0
	v_mov_b32_e32 v34, v226
	v_mov_b32_e32 v35, v227
	v_permlane16_swap_b32_e32 v65, v0
	v_permlane16_swap_b32_e32 v34, v226
	v_permlane16_swap_b32_e32 v35, v227
	v_add_f32_e32 v0, v65, v0
	v_add_f32_e32 v226, v34, v226
	v_add_f32_e32 v227, v35, v227
	s_and_saveexec_b64 s[0:1], s[4:5]
	ds_write_b32 v177, v0 offset:36972
	ds_write_b32 v177, v226 offset:36992
	ds_write_b32 v177, v227 offset:36996
	s_or_b64 exec, exec, s[0:1]
	v_mul_f32_e32 v0, v36, v140
	v_mul_f32_e32 v226, v37, v140
	v_mul_f32_e32 v227, v38, v140
	v_mov_b32_dpp v0, v0 row_ror:8 row_mask:0xf bank_mask:0xf
	v_mov_b32_dpp v226, v226 row_ror:8 row_mask:0xf bank_mask:0xf
	v_mov_b32_dpp v227, v227 row_ror:8 row_mask:0xf bank_mask:0xf
	v_fmac_f32_e32 v0, v36, v140
	v_fmac_f32_e32 v226, v37, v140
	v_fmac_f32_e32 v227, v38, v140
	v_mov_b32_e32 v36, v0
	v_mov_b32_e32 v37, v226
	v_mov_b32_e32 v38, v227
	v_permlane16_swap_b32_e32 v36, v0
	v_permlane16_swap_b32_e32 v37, v226
	v_permlane16_swap_b32_e32 v38, v227
	v_add_f32_e32 v0, v36, v0
	v_add_f32_e32 v226, v37, v226
	v_add_f32_e32 v227, v38, v227
	s_and_saveexec_b64 s[0:1], s[4:5]
	ds_write_b32 v177, v0 offset:37000
	ds_write_b32 v177, v226 offset:37004
	ds_write_b32 v177, v227 offset:37024
	s_or_b64 exec, exec, s[0:1]
	v_mul_f32_e32 v0, v39, v140
	v_mul_f32_e32 v226, v40, v140
	v_mul_f32_e32 v227, v41, v140
	v_mov_b32_dpp v0, v0 row_ror:8 row_mask:0xf bank_mask:0xf
	v_mov_b32_dpp v226, v226 row_ror:8 row_mask:0xf bank_mask:0xf
	v_mov_b32_dpp v227, v227 row_ror:8 row_mask:0xf bank_mask:0xf
	v_fmac_f32_e32 v0, v39, v140
	v_fmac_f32_e32 v226, v40, v140
	v_fmac_f32_e32 v227, v41, v140
	v_mov_b32_e32 v39, v0
	v_mov_b32_e32 v40, v226
	v_mov_b32_e32 v41, v227
	v_permlane16_swap_b32_e32 v39, v0
	v_permlane16_swap_b32_e32 v40, v226
	v_permlane16_swap_b32_e32 v41, v227
	v_add_f32_e32 v0, v39, v0
	v_add_f32_e32 v226, v40, v226
	v_add_f32_e32 v227, v41, v227
	s_and_saveexec_b64 s[0:1], s[4:5]
	ds_write_b32 v177, v0 offset:37028
	ds_write_b32 v177, v226 offset:37032
	ds_write_b32 v177, v227 offset:37036
	s_or_b64 exec, exec, s[0:1]
	v_mul_f32_e32 v0, v42, v140
	v_mul_f32_e32 v226, v43, v140
	v_mul_f32_e32 v227, v44, v140
	v_mov_b32_dpp v0, v0 row_ror:8 row_mask:0xf bank_mask:0xf
	v_mov_b32_dpp v226, v226 row_ror:8 row_mask:0xf bank_mask:0xf
	v_mov_b32_dpp v227, v227 row_ror:8 row_mask:0xf bank_mask:0xf
	v_fmac_f32_e32 v0, v42, v140
	v_fmac_f32_e32 v226, v43, v140
	v_fmac_f32_e32 v227, v44, v140
	v_mov_b32_e32 v42, v0
	v_mov_b32_e32 v43, v226
	v_mov_b32_e32 v44, v227
	v_permlane16_swap_b32_e32 v42, v0
	v_permlane16_swap_b32_e32 v43, v226
	v_permlane16_swap_b32_e32 v44, v227
	v_add_f32_e32 v0, v42, v0
	v_add_f32_e32 v226, v43, v226
	v_add_f32_e32 v227, v44, v227
	s_and_saveexec_b64 s[0:1], s[4:5]
	ds_write_b32 v177, v0 offset:37056
	ds_write_b32 v177, v226 offset:37060
	ds_write_b32 v177, v227 offset:37064
	s_or_b64 exec, exec, s[0:1]
	v_mul_f32_e32 v0, v45, v140
	v_mul_f32_e32 v226, v46, v140
	v_mul_f32_e32 v227, v47, v140
	v_mov_b32_dpp v0, v0 row_ror:8 row_mask:0xf bank_mask:0xf
	v_mov_b32_dpp v226, v226 row_ror:8 row_mask:0xf bank_mask:0xf
	v_mov_b32_dpp v227, v227 row_ror:8 row_mask:0xf bank_mask:0xf
	v_fmac_f32_e32 v0, v45, v140
	v_fmac_f32_e32 v226, v46, v140
	v_fmac_f32_e32 v227, v47, v140
	v_mov_b32_e32 v45, v0
	v_mov_b32_e32 v46, v226
	v_mov_b32_e32 v47, v227
	v_permlane16_swap_b32_e32 v45, v0
	v_permlane16_swap_b32_e32 v46, v226
	v_permlane16_swap_b32_e32 v47, v227
	v_add_f32_e32 v0, v45, v0
	v_add_f32_e32 v226, v46, v226
	v_add_f32_e32 v227, v47, v227
	s_and_saveexec_b64 s[0:1], s[4:5]
	ds_write_b32 v177, v0 offset:37068
	ds_write_b32 v177, v226 offset:37088
	ds_write_b32 v177, v227 offset:37092
	s_or_b64 exec, exec, s[0:1]
	v_mul_f32_e32 v0, v48, v140
	v_mul_f32_e32 v226, v49, v140
	s_nop 0
	v_mov_b32_dpp v0, v0 row_ror:8 row_mask:0xf bank_mask:0xf
	v_mov_b32_dpp v226, v226 row_ror:8 row_mask:0xf bank_mask:0xf
	v_fmac_f32_e32 v0, v48, v140
	v_fmac_f32_e32 v226, v49, v140
	v_mov_b32_e32 v48, v0
	v_mov_b32_e32 v49, v226
	s_nop 0
	v_permlane16_swap_b32_e32 v48, v0
	v_permlane16_swap_b32_e32 v49, v226
	v_add_f32_e32 v0, v48, v0
	v_add_f32_e32 v226, v49, v226
	s_and_saveexec_b64 s[0:1], s[4:5]
	ds_write_b32 v177, v0 offset:37096
	ds_write_b32 v177, v226 offset:37100
	s_or_b64 exec, exec, s[0:1]
	s_waitcnt lgkmcnt(0)
	v_cmp_eq_u32_e32 vcc, s67, v168
	s_or_b64 s[0:1], s[6:7], vcc
	v_cmp_eq_u32_e32 vcc, s67, v207
	s_or_b64 vcc, s[0:1], vcc
	v_cmp_lt_i32_e64 s[0:1], s67, v168
	s_cmp_lt_u32 s67, 16
	s_cbranch_scc0 .Ltopk_full
	s_not_b64 s[20:21], s[0:1]
	s_mov_b64 s[86:87], s[20:21]
	s_mov_b64 s[24:25], s[20:21]
	s_mov_b64 s[26:27], s[20:21]
	s_mov_b64 s[28:29], s[20:21]
	s_mov_b64 s[30:31], s[20:21]
	s_mov_b64 s[10:11], s[20:21]
	s_mov_b64 s[8:9], s[20:21]
	s_and_saveexec_b64 s[12:13], s[6:7]
	v_mov_b32_e32 v0, s70
	v_mov_b64_e32 v[34:35], s[20:21]
	ds_write_b64 v0, v[34:35] offset:53248
	ds_write_b64 v0, v[34:35] offset:53256
	ds_write_b64 v0, v[34:35] offset:53264
	ds_write_b64 v0, v[34:35] offset:53272
	ds_write_b64 v0, v[34:35] offset:53280
	ds_write_b64 v0, v[34:35] offset:53288
	ds_write_b64 v0, v[34:35] offset:53296
	ds_write_b64 v0, v[34:35] offset:53304
	s_or_b64 exec, exec, s[12:13]
	s_branch .Ltopk_end
.Ltopk_full:
	ds_read_b32 v0, v206 offset:36864
	ds_read_b32 v34, v206 offset:37120
	ds_read_b32 v35, v206 offset:37376
	ds_read_b32 v226, v206 offset:37632
	s_mov_b32 s28, 0
	s_mov_b32 s29, 0
	s_mov_b32 s30, 0
	s_mov_b32 s31, 0
	s_mov_b32 s18, 0x40000000
	s_waitcnt lgkmcnt(0)
	v_cndmask_b32_e32 v0, v0, v231, vcc
	v_cndmask_b32_e32 v34, v34, v231, vcc
	v_cndmask_b32_e32 v35, v35, v231, vcc
	v_cndmask_b32_e32 v226, v226, v231, vcc
	v_and_b32_e32 v0, 0x7fffffff, v0
	v_and_b32_e32 v34, 0x7fffffff, v34
	v_and_b32_e32 v35, 0x7fffffff, v35
	v_and_b32_e32 v226, 0x7fffffff, v226
	v_cndmask_b32_e64 v0, v0, -1.0, s[0:1]
	v_cndmask_b32_e64 v34, v34, -1.0, s[0:1]
	v_cndmask_b32_e64 v35, v35, -1.0, s[0:1]
	v_cndmask_b32_e64 v226, v226, -1.0, s[0:1]

.Ltopk_end:
	s_and_saveexec_b64 s[0:1], s[6:7]
	s_cbranch_execz .LBB0_345
	s_or_b64 s[12:13], s[86:87], s[20:21]
	s_or_b64 s[12:13], s[12:13], s[24:25]
	s_or_b64 s[12:13], s[12:13], s[26:27]
	s_or_b64 s[12:13], s[12:13], s[28:29]
	s_or_b64 s[12:13], s[12:13], s[30:31]
	v_mbcnt_lo_u32_b32 v0, exec_lo, 0
	s_or_b64 s[10:11], s[12:13], s[10:11]
	v_mbcnt_hi_u32_b32 v0, exec_hi, v0
	s_or_b64 s[8:9], s[10:11], s[8:9]
	v_cmp_eq_u32_e32 vcc, 0, v0
	s_and_saveexec_b64 s[10:11], vcc
	v_mov_b32_e32 v0, s8
	ds_or_b32 v1, v0 offset:53760
	s_or_b64 exec, exec, s[10:11]
	v_mbcnt_lo_u32_b32 v0, exec_lo, 0
	v_mbcnt_hi_u32_b32 v0, exec_hi, v0
	v_cmp_eq_u32_e32 vcc, 0, v0
	s_and_b64 exec, exec, vcc
	v_mov_b32_e32 v0, s9
	ds_or_b32 v1, v0 offset:53764
